# plus LN0: adaLN shift/scale vectors of the first condition computed before the row loop with batched loads
# speedup vs baseline: 1.0122x; 1.0102x over previous
.LBB0_1140:
	s_or_b64 exec, exec, s[24:25]
	v_ashrrev_i32_e32 v0, 6, v2
	v_add_u32_e32 v0, s72, v0
	v_readlane_b32 s24, v235, 38
	s_nop 1
	v_mul_lo_u32 v0, s24, v0
	v_add_u32_e32 v1, s24, v0
	v_min_i32_e32 v101, 0x5000, v1
	v_cmp_lt_i32_e32 vcc, v0, v101
	s_and_saveexec_b64 s[24:25], vcc
	s_cbranch_execz .LBB0_1161
	v_lshlrev_b32_e32 v1, 2, v2
	v_and_b32_e32 v100, 0xfc, v1
	s_mov_b64 s[26:27], 0x2e98000
	v_lshlrev_b32_e32 v6, 1, v100
	v_mov_b32_e32 v7, v3
	v_lshl_add_u64 v[102:103], v[4:5], 0, s[26:27]
	v_lshl_add_u64 v[6:7], v[4:5], 0, v[6:7]
	s_mov_b64 s[26:27], 0x8208000
	v_ashrrev_i32_e32 v1, 31, v0
	v_lshl_add_u64 v[104:105], v[6:7], 0, s[26:27]
	v_lshlrev_b64 v[6:7], 11, v[0:1]
	v_and_b32_e32 v1, 63, v2
	v_lshl_or_b32 v6, v1, 3, v6
	v_lshl_add_u64 v[4:5], v[4:5], 0, v[6:7]
	s_mov_b64 s[26:27], 0x8208600
	v_mov_b32_e32 v182, v3
	v_mov_b32_e32 v160, v3
	v_mov_b32_e32 v161, v3
	v_mov_b32_e32 v154, v183
	v_mov_b32_e32 v155, v183
	v_mov_b32_e32 v184, -1
	v_add_u32_e32 v107, -1, v101
	v_or_b32_e32 v106, 0x400, v100
	v_or_b32_e32 v109, 1, v100
	v_or_b32_e32 v108, 0x401, v100
	v_or_b32_e32 v111, 3, v100
	v_or_b32_e32 v110, 0x403, v100
	v_or_b32_e32 v113, 0x100, v100
	v_or_b32_e32 v112, 0x500, v100
	v_or_b32_e32 v115, 0x101, v100
	v_or_b32_e32 v114, 0x501, v100
	v_or_b32_e32 v117, 0x103, v100
	v_or_b32_e32 v116, 0x503, v100
	v_or_b32_e32 v119, 0x200, v100
	v_or_b32_e32 v118, 0x600, v100
	v_or_b32_e32 v121, 0x201, v100
	v_or_b32_e32 v120, 0x601, v100
	v_or_b32_e32 v123, 0x203, v100
	v_or_b32_e32 v122, 0x603, v100
	v_or_b32_e32 v125, 0x300, v100
	v_or_b32_e32 v124, 0x700, v100
	v_or_b32_e32 v127, 0x301, v100
	v_or_b32_e32 v126, 0x702, v100
	v_or_b32_e32 v190, 0x303, v100
	v_lshl_add_u64 v[128:129], v[4:5], 0, s[26:27]
	v_mov_b32_e32 v166, v183
	v_mov_b32_e32 v167, v3
	s_mov_b64 s[26:27], 0
	v_mov_b64_e32 v[94:95], v[154:155]
	v_mov_b64_e32 v[146:147], v[154:155]
	v_mov_b64_e32 v[90:91], v[154:155]
	v_mov_b64_e32 v[134:135], v[154:155]
	v_mov_b64_e32 v[88:89], v[160:161]
	v_mov_b64_e32 v[98:99], v[160:161]
	v_mov_b64_e32 v[86:87], v[160:161]
	v_mov_b64_e32 v[96:97], v[160:161]
	v_mov_b64_e32 v[92:93], v[160:161]
	v_mov_b64_e32 v[132:133], v[160:161]
	v_mov_b64_e32 v[84:85], v[182:183]
	v_mov_b64_e32 v[158:159], v[154:155]
	v_mov_b64_e32 v[168:169], v[154:155]
	v_add_u32_e32 v1, 0xfffff000, v0
	v_cmp_gt_i32_e32 vcc, 0x1000, v0
	v_lshrrev_b32_e32 v1, 12, v1
	v_add_u32_e32 v1, 1, v1
	s_load_dwordx2 s[28:29], s[22:23], 0x40
	v_cndmask_b32_e64 v1, v1, 0, vcc
	v_mov_b32_e32 v184, v1
	v_mul_u32_u24_e32 v2, 0x1800, v1
	v_add_u32_e32 v2, v2, v100
	v_lshlrev_b32_e32 v2, 2, v2
	v_lshlrev_b32_e32 v136, 2, v100
	v_lshl_add_u64 v[138:139], v[102:103], 0, v[2:3]
	s_mov_b64 s[42:43], 0x1e000
	v_lshl_add_u64 v[140:141], v[138:139], 0, s[42:43]
	s_mov_b64 s[42:43], 0x3c000
	v_lshl_add_u64 v[142:143], v[138:139], 0, s[42:43]
	s_mov_b64 s[42:43], 0x5a000
	v_lshl_add_u64 v[144:145], v[138:139], 0, s[42:43]
	s_waitcnt lgkmcnt(0)
	global_load_dwordx4 v[4:7], v136, s[28:29]
	global_load_dwordx4 v[8:11], v[138:139], off
	global_load_dwordx4 v[12:15], v[140:141], off
	global_load_dwordx4 v[16:19], v[142:143], off
	global_load_dwordx4 v[20:23], v[144:145], off
	global_load_dwordx4 v[24:27], v136, s[28:29] offset:1024
	global_load_dwordx4 v[28:31], v[138:139], off offset:1024
	global_load_dwordx4 v[32:35], v[140:141], off offset:1024
	global_load_dwordx4 v[36:39], v[142:143], off offset:1024
	global_load_dwordx4 v[40:43], v[144:145], off offset:1024
	global_load_dwordx4 v[44:47], v136, s[28:29] offset:2048
	global_load_dwordx4 v[48:51], v[138:139], off offset:2048
	global_load_dwordx4 v[52:55], v[140:141], off offset:2048
	global_load_dwordx4 v[56:59], v[142:143], off offset:2048
	global_load_dwordx4 v[60:63], v[144:145], off offset:2048
	global_load_dwordx4 v[64:67], v136, s[28:29] offset:3072
	global_load_dwordx4 v[68:71], v[138:139], off offset:3072
	global_load_dwordx4 v[72:75], v[140:141], off offset:3072
	global_load_dwordx4 v[76:79], v[142:143], off offset:3072
	global_load_dwordx4 v[80:83], v[144:145], off offset:3072
	s_waitcnt vmcnt(0)
	v_add_f32_e32 v84, v4, v8
	v_add_f32_e32 v132, v5, v9
	v_add_f32_e32 v133, v6, v10
	v_add_f32_e32 v93, v7, v11
	v_add_f32_e32 v84, v84, v12
	v_add_f32_e32 v132, v132, v13
	v_add_f32_e32 v133, v133, v14
	v_add_f32_e32 v93, v93, v15
	v_add_f32_e32 v84, v84, v16
	v_add_f32_e32 v132, v132, v17
	v_add_f32_e32 v133, v133, v18
	v_add_f32_e32 v93, v93, v19
	v_add_f32_e32 v84, v84, v20
	v_add_f32_e32 v132, v132, v21
	v_add_f32_e32 v133, v133, v22
	v_add_f32_e32 v93, v93, v23
	v_add_f32_e32 v92, v24, v28
	v_add_f32_e32 v96, v25, v29
	v_add_f32_e32 v97, v26, v30
	v_add_f32_e32 v87, v27, v31
	v_add_f32_e32 v92, v92, v32
	v_add_f32_e32 v96, v96, v33
	v_add_f32_e32 v97, v97, v34
	v_add_f32_e32 v87, v87, v35
	v_add_f32_e32 v92, v92, v36
	v_add_f32_e32 v96, v96, v37
	v_add_f32_e32 v97, v97, v38
	v_add_f32_e32 v87, v87, v39
	v_add_f32_e32 v92, v92, v40
	v_add_f32_e32 v96, v96, v41
	v_add_f32_e32 v97, v97, v42
	v_add_f32_e32 v87, v87, v43
	v_add_f32_e32 v86, v44, v48
	v_add_f32_e32 v98, v45, v49
	v_add_f32_e32 v99, v46, v50
	v_add_f32_e32 v89, v47, v51
	v_add_f32_e32 v86, v86, v52
	v_add_f32_e32 v98, v98, v53
	v_add_f32_e32 v99, v99, v54
	v_add_f32_e32 v89, v89, v55
	v_add_f32_e32 v86, v86, v56
	v_add_f32_e32 v98, v98, v57
	v_add_f32_e32 v99, v99, v58
	v_add_f32_e32 v89, v89, v59
	v_add_f32_e32 v86, v86, v60
	v_add_f32_e32 v98, v98, v61
	v_add_f32_e32 v99, v99, v62
	v_add_f32_e32 v89, v89, v63
	v_add_f32_e32 v88, v64, v68
	v_add_f32_e32 v160, v65, v69
	v_add_f32_e32 v161, v66, v70
	v_add_f32_e32 v167, v67, v71
	v_add_f32_e32 v88, v88, v72
	v_add_f32_e32 v160, v160, v73
	v_add_f32_e32 v161, v161, v74
	v_add_f32_e32 v167, v167, v75
	v_add_f32_e32 v88, v88, v76
	v_add_f32_e32 v160, v160, v77
	v_add_f32_e32 v161, v161, v78
	v_add_f32_e32 v167, v167, v79
	v_add_f32_e32 v88, v88, v80
	v_add_f32_e32 v160, v160, v81
	v_add_f32_e32 v161, v161, v82
	v_add_f32_e32 v167, v167, v83
	v_add_u32_e32 v136, 0x1000, v136
	v_lshl_add_u64 v[138:139], v[138:139], 0, s[56:57]
	v_lshl_add_u64 v[140:141], v[140:141], 0, s[56:57]
	v_lshl_add_u64 v[142:143], v[142:143], 0, s[56:57]
	v_lshl_add_u64 v[144:145], v[144:145], 0, s[56:57]
	global_load_dwordx4 v[4:7], v136, s[28:29]
	global_load_dwordx4 v[8:11], v[138:139], off
	global_load_dwordx4 v[12:15], v[140:141], off
	global_load_dwordx4 v[16:19], v[142:143], off
	global_load_dwordx4 v[20:23], v[144:145], off
	global_load_dwordx4 v[24:27], v136, s[28:29] offset:1024
	global_load_dwordx4 v[28:31], v[138:139], off offset:1024
	global_load_dwordx4 v[32:35], v[140:141], off offset:1024
	global_load_dwordx4 v[36:39], v[142:143], off offset:1024
	global_load_dwordx4 v[40:43], v[144:145], off offset:1024
	global_load_dwordx4 v[44:47], v136, s[28:29] offset:2048
	global_load_dwordx4 v[48:51], v[138:139], off offset:2048
	global_load_dwordx4 v[52:55], v[140:141], off offset:2048
	global_load_dwordx4 v[56:59], v[142:143], off offset:2048
	global_load_dwordx4 v[60:63], v[144:145], off offset:2048
	global_load_dwordx4 v[64:67], v136, s[28:29] offset:3072
	global_load_dwordx4 v[68:71], v[138:139], off offset:3072
	global_load_dwordx4 v[72:75], v[140:141], off offset:3072
	global_load_dwordx4 v[76:79], v[142:143], off offset:3072
	global_load_dwordx4 v[80:83], v[144:145], off offset:3072
	s_waitcnt vmcnt(0)
	v_add_f32_e32 v166, v4, v8
	v_add_f32_e32 v134, v5, v9
	v_add_f32_e32 v135, v6, v10
	v_add_f32_e32 v91, v7, v11
	v_add_f32_e32 v166, v166, v12
	v_add_f32_e32 v134, v134, v13
	v_add_f32_e32 v135, v135, v14
	v_add_f32_e32 v91, v91, v15
	v_add_f32_e32 v166, v166, v16
	v_add_f32_e32 v134, v134, v17
	v_add_f32_e32 v135, v135, v18
	v_add_f32_e32 v91, v91, v19
	v_add_f32_e32 v166, v166, v20
	v_add_f32_e32 v134, v134, v21
	v_add_f32_e32 v135, v135, v22
	v_add_f32_e32 v91, v91, v23
	v_add_f32_e32 v166, 1.0, v166
	v_add_f32_e32 v134, 1.0, v134
	v_add_f32_e32 v135, 1.0, v135
	v_add_f32_e32 v91, 1.0, v91
	v_add_f32_e32 v90, v24, v28
	v_add_f32_e32 v146, v25, v29
	v_add_f32_e32 v147, v26, v30
	v_add_f32_e32 v95, v27, v31
	v_add_f32_e32 v90, v90, v32
	v_add_f32_e32 v146, v146, v33
	v_add_f32_e32 v147, v147, v34
	v_add_f32_e32 v95, v95, v35
	v_add_f32_e32 v90, v90, v36
	v_add_f32_e32 v146, v146, v37
	v_add_f32_e32 v147, v147, v38
	v_add_f32_e32 v95, v95, v39
	v_add_f32_e32 v90, v90, v40
	v_add_f32_e32 v146, v146, v41
	v_add_f32_e32 v147, v147, v42
	v_add_f32_e32 v95, v95, v43
	v_add_f32_e32 v90, 1.0, v90
	v_add_f32_e32 v146, 1.0, v146
	v_add_f32_e32 v147, 1.0, v147
	v_add_f32_e32 v95, 1.0, v95
	v_add_f32_e32 v94, v44, v48
	v_add_f32_e32 v154, v45, v49
	v_add_f32_e32 v155, v46, v50
	v_add_f32_e32 v85, v47, v51
	v_add_f32_e32 v94, v94, v52
	v_add_f32_e32 v154, v154, v53
	v_add_f32_e32 v155, v155, v54
	v_add_f32_e32 v85, v85, v55
	v_add_f32_e32 v94, v94, v56
	v_add_f32_e32 v154, v154, v57
	v_add_f32_e32 v155, v155, v58
	v_add_f32_e32 v85, v85, v59
	v_add_f32_e32 v94, v94, v60
	v_add_f32_e32 v154, v154, v61
	v_add_f32_e32 v155, v155, v62
	v_add_f32_e32 v85, v85, v63
	v_add_f32_e32 v94, 1.0, v94
	v_add_f32_e32 v154, 1.0, v154
	v_add_f32_e32 v155, 1.0, v155
	v_add_f32_e32 v85, 1.0, v85
	v_add_f32_e32 v158, v64, v68
	v_add_f32_e32 v159, v65, v69
	v_add_f32_e32 v168, v66, v70
	v_add_f32_e32 v169, v67, v71
	v_add_f32_e32 v158, v158, v72
	v_add_f32_e32 v159, v159, v73
	v_add_f32_e32 v168, v168, v74
	v_add_f32_e32 v169, v169, v75
	v_add_f32_e32 v158, v158, v76
	v_add_f32_e32 v159, v159, v77
	v_add_f32_e32 v168, v168, v78
	v_add_f32_e32 v169, v169, v79
	v_add_f32_e32 v158, v158, v80
	v_add_f32_e32 v159, v159, v81
	v_add_f32_e32 v168, v168, v82
	v_add_f32_e32 v169, v169, v83
	v_add_f32_e32 v158, 1.0, v158
	v_add_f32_e32 v159, 1.0, v159
	v_add_f32_e32 v168, 1.0, v168
	v_add_f32_e32 v169, 1.0, v169
	s_branch .LBB0_1144
